# attention loop: deeper K-fragment prefetch combined with per-operand counted LDS waits in the PV sections
# speedup vs baseline: 1.0095x; 1.0095x over previous
; #define SBAR() __builtin_amdgcn_sched_barrier(0)
; __device__ __forceinline__ void finishSM(f32x16& p0, f32x16& p1, float alpha, float& l_reg, bf16x8& pa0, bf16x8& pa1, bf16x8& pa2, bf16x8& pa3) {
; #pragma unroll
;   for (int r = 0; r < 16; ++r) p1[r] = __builtin_amdgcn_exp2f(p1[r]);
;   float ps = 0;
; #pragma unroll
;   for (int r = 0; r < 16; ++r) ps += p0[r];
; #pragma unroll
;   for (int r = 0; r < 16; ++r) ps += p1[r];
;   { auto rr = __builtin_amdgcn_permlane32_swap(__float_as_uint(ps), __float_as_uint(ps), false, false);
;     ps = __uint_as_float(rr[0]) + __uint_as_float(rr[1]); }
;   l_reg = l_reg * alpha + ps;
;     ...
;   PK4(p0, 0, pa0); PK4(p0, 8, pa1); PK4(p1, 0, pa2); PK4(p1, 8, pa3);
;     ...
; }
; __device__ __forceinline__ void qkt(f32x16& p0, f32x16& p1, const bf16_t* Ks, const bf16x8* qr, int r32, int hi) {
;   p0 = f32x16{}; p1 = f32x16{};
; #pragma unroll
;   for (int d0 = 0; d0 < 8; ++d0) { int cb = (d0 * 16 + hi * 8) * 2;
;     bf16x8 b0 = *reinterpret_cast<const bf16x8*>((const char*)Ks + KSWZ(r32, cb));
;     bf16x8 b1 = *reinterpret_cast<const bf16x8*>((const char*)Ks + KSWZ(32 + r32, cb));
;     p0 = __builtin_amdgcn_mfma_f32_32x32x16_bf16(b0, qr[d0], p0, 0, 0, 0);
;     p1 = __builtin_amdgcn_mfma_f32_32x32x16_bf16(b1, qr[d0], p1, 0, 0, 0); }
; template <int D0> __device__ __forceinline__ void pv_one(f32x16& od, int vb, bf16x8 pa0, bf16x8 pa1, bf16x8 pa2, bf16x8 pa3) {
;   const s16x4 l0 = tr_read<v_rd_off(D0, 0, 0)>(vb), h0 = tr_read<v_rd_off(D0, 0, 1)>(vb), l1 = tr_read<v_rd_off(D0, 1, 0)>(vb), h1 = tr_read<v_rd_off(D0, 1, 1)>(vb);
;   const s16x4 l2 = tr_read<v_rd_off(D0, 2, 0)>(vb), h2 = tr_read<v_rd_off(D0, 2, 1)>(vb), l3 = tr_read<v_rd_off(D0, 3, 0)>(vb), h3 = tr_read<v_rd_off(D0, 3, 1)>(vb);
;   asm volatile("s_waitcnt lgkmcnt(0)" ::: "memory"); SBAR();
.LBB0_444:
	ds_read_b128 v[64:67], v204 offset:49152
	ds_read_b128 v[68:71], v204 offset:57344
	ds_read_b128 v[218:221], v205 offset:49152
	ds_read_b128 v[222:225], v205 offset:57344
	ds_read_b128 v[248:251], v206 offset:49152
	ds_read_b128 v[252:255], v206 offset:57344
	v_add_f32_e32 v161, 0, v175
	v_add_f32_e32 v161, v191, v161
	s_waitcnt lgkmcnt(5)
	v_mfma_f32_32x32x16_bf16 v[80:95], v[64:67], v[124:127], 0
	v_add_f32_e32 v161, v173, v161
	v_add_f32_e32 v161, v190, v161
	v_add_f32_e32 v161, v172, v161
	v_add_f32_e32 v161, v174, v161
	v_add_f32_e32 v161, v170, v161
	v_add_f32_e32 v161, v171, v161
	v_add_f32_e32 v161, v167, v161
	s_waitcnt lgkmcnt(4)
	v_mfma_f32_32x32x16_bf16 v[64:79], v[68:71], v[124:127], 0
	v_add_f32_e32 v161, v169, v161
	v_add_f32_e32 v161, v166, v161
	v_add_f32_e32 v161, v168, v161
	v_exp_f32_e32 v154, v154
	v_add_f32_e32 v161, v163, v161
	v_exp_f32_e32 v155, v155
	v_add_f32_e32 v161, v165, v161
	s_waitcnt lgkmcnt(3)
	v_mfma_f32_32x32x16_bf16 v[80:95], v[218:221], v[120:123], v[80:95]
	v_exp_f32_e32 v152, v152
	v_add_f32_e32 v161, v162, v161
	v_exp_f32_e32 v153, v153
	v_add_f32_e32 v161, v164, v161
	v_exp_f32_e32 v148, v148
	v_add_f32_e32 v161, v154, v161
	v_exp_f32_e32 v149, v149
	s_waitcnt lgkmcnt(2)
	v_mfma_f32_32x32x16_bf16 v[64:79], v[222:225], v[120:123], v[64:79]
	ds_read_b128 v[218:221], v207 offset:49152
	ds_read_b128 v[222:225], v207 offset:57344
	v_add_f32_e32 v161, v155, v161
	v_exp_f32_e32 v146, v146
	v_add_f32_e32 v161, v152, v161
	v_exp_f32_e32 v147, v147
	v_add_f32_e32 v161, v153, v161
	v_exp_f32_e32 v144, v144
	s_waitcnt lgkmcnt(3)
	v_mfma_f32_32x32x16_bf16 v[80:95], v[248:251], v[116:119], v[80:95]
	v_add_f32_e32 v161, v148, v161
	v_exp_f32_e32 v145, v145
	v_add_f32_e32 v161, v149, v161
	v_exp_f32_e32 v158, v158
	v_add_f32_e32 v161, v146, v161
	v_exp_f32_e32 v159, v159
	v_add_f32_e32 v161, v147, v161
	s_waitcnt lgkmcnt(2)
	v_mfma_f32_32x32x16_bf16 v[64:79], v[252:255], v[116:119], v[64:79]
	ds_read_b128 v[248:251], v208 offset:49152
	ds_read_b128 v[252:255], v208 offset:57344
	v_exp_f32_e32 v156, v156
	v_add_f32_e32 v161, v144, v161
	v_exp_f32_e32 v157, v157
	v_add_f32_e32 v161, v145, v161
	v_exp_f32_e32 v150, v150
	v_add_f32_e32 v161, v158, v161
	s_waitcnt lgkmcnt(3)
	v_mfma_f32_32x32x16_bf16 v[80:95], v[218:221], v[112:115], v[80:95]
	v_exp_f32_e32 v151, v151
	v_add_f32_e32 v161, v159, v161
	v_add_f32_e32 v161, v156, v161
	v_add_f32_e32 v161, v157, v161
	v_add_f32_e32 v161, v150, v161
	v_add_f32_e32 v215, v151, v161
	s_waitcnt lgkmcnt(2)
	v_mfma_f32_32x32x16_bf16 v[64:79], v[222:225], v[112:115], v[64:79]
	ds_read_b128 v[218:221], v209 offset:49152
	ds_read_b128 v[222:225], v209 offset:57344
	s_waitcnt lgkmcnt(3)
	v_mfma_f32_32x32x16_bf16 v[80:95], v[248:251], v[108:111], v[80:95]
	s_waitcnt lgkmcnt(2)
	v_mfma_f32_32x32x16_bf16 v[64:79], v[252:255], v[108:111], v[64:79]
	ds_read_b128 v[248:251], v210 offset:49152
	ds_read_b128 v[252:255], v210 offset:57344
	s_waitcnt lgkmcnt(3)
	v_mfma_f32_32x32x16_bf16 v[80:95], v[218:221], v[104:107], v[80:95]
	s_waitcnt lgkmcnt(2)
	v_mfma_f32_32x32x16_bf16 v[64:79], v[222:225], v[104:107], v[64:79]
	ds_read_b128 v[218:221], v211 offset:49152
	ds_read_b128 v[222:225], v211 offset:57344
	s_waitcnt lgkmcnt(3)
	v_mfma_f32_32x32x16_bf16 v[80:95], v[248:251], v[100:103], v[80:95]
	s_waitcnt lgkmcnt(2)
	v_mfma_f32_32x32x16_bf16 v[64:79], v[252:255], v[100:103], v[64:79]
	s_waitcnt lgkmcnt(1)
	v_mfma_f32_32x32x16_bf16 v[80:95], v[218:221], v[96:99], v[80:95]
	v_mov_b32_e32 v218, v215
	s_nop 1
	v_permlane32_swap_b32_e32 v215, v218
	v_cvt_pk_bf16_f32 v220, v175, v191
	v_cvt_pk_bf16_f32 v221, v173, v190
	s_waitcnt lgkmcnt(0)
	v_mfma_f32_32x32x16_bf16 v[64:79], v[222:225], v[96:99], v[64:79]
	v_cvt_pk_bf16_f32 v222, v172, v174
	v_cvt_pk_bf16_f32 v223, v170, v171
	v_cvt_pk_bf16_f32 v170, v167, v169
	v_cvt_pk_bf16_f32 v171, v166, v168
	v_cvt_pk_bf16_f32 v172, v163, v165
	v_cvt_pk_bf16_f32 v173, v162, v164
	v_cvt_pk_bf16_f32 v162, v154, v155
	v_cvt_pk_bf16_f32 v163, v152, v153
	v_cvt_pk_bf16_f32 v164, v148, v149
	v_cvt_pk_bf16_f32 v165, v146, v147
	v_cvt_pk_bf16_f32 v166, v144, v145
	v_cvt_pk_bf16_f32 v167, v158, v159
	v_cvt_pk_bf16_f32 v168, v156, v157
	v_cvt_pk_bf16_f32 v169, v150, v151
	s_nop 0
	v_permlane32_swap_b32_e32 v220, v222
	v_permlane32_swap_b32_e32 v221, v223
	v_permlane32_swap_b32_e32 v170, v172
	v_permlane32_swap_b32_e32 v171, v173
	v_permlane32_swap_b32_e32 v162, v164
	v_permlane32_swap_b32_e32 v163, v165
	v_permlane32_swap_b32_e32 v166, v168
	v_permlane32_swap_b32_e32 v167, v169
	v_lshl_add_u64 v[192:193], s[18:19], 0, v[180:181]
	v_add_co_u32_e32 v144, vcc, s68, v192
	v_lshl_add_u64 v[190:191], s[18:19], 0, v[182:183]
	s_nop 0
	v_addc_co_u32_e32 v145, vcc, 0, v193, vcc
	v_add_co_u32_e32 v148, vcc, s68, v190
	s_nop 1
	v_addc_co_u32_e32 v149, vcc, 0, v191, vcc
	v_add_co_u32_e32 v152, vcc, s69, v192
	global_load_dwordx4 v[144:147], v[144:145], off
	s_nop 0
	global_load_dwordx4 v[148:151], v[148:149], off
	v_addc_co_u32_e32 v153, vcc, 0, v193, vcc
	v_add_co_u32_e32 v156, vcc, s69, v190
	s_nop 1
	v_addc_co_u32_e32 v157, vcc, 0, v191, vcc
	global_load_dwordx4 v[152:155], v[152:153], off
	s_nop 0
	global_load_dwordx4 v[156:159], v[156:157], off
	ds_read_b64_tr_b16 v[224:225], v196 offset:0
	ds_read_b64_tr_b16 v[226:227], v196 offset:0x800
	ds_read_b64_tr_b16 v[228:229], v196 offset:0x1000
	ds_read_b64_tr_b16 v[230:231], v196 offset:0x1800
	ds_read_b64_tr_b16 v[232:233], v196 offset:0x200
	ds_read_b64_tr_b16 v[234:235], v196 offset:0xa00
	ds_read_b64_tr_b16 v[236:237], v196 offset:0x1200
	ds_read_b64_tr_b16 v[238:239], v196 offset:0x1a00
	s_nop 0
	s_waitcnt lgkmcnt(6)
; __device__ __forceinline__ void partialSM(f32x16& p0, f32x16& p1, float& m_reg, float& mn, float& alpha) {
;   constexpr float C = SCALE * 1.4426950408889634f;
;   float pmax = p0[0];
; #pragma unroll
;   for (int r = 1; r < 16; ++r) pmax = fmaxf(pmax, p0[r]);
; #pragma unroll
;   for (int r = 0; r < 16; ++r) pmax = fmaxf(pmax, p1[r]);
;   { auto rr = __builtin_amdgcn_permlane32_swap(__float_as_uint(pmax), __float_as_uint(pmax), false, false);
;     pmax = fmaxf(__uint_as_float(rr[0]), __uint_as_float(rr[1])); }
; template <int DA, int DB> __device__ __forceinline__ void pv_pair(f32x16& oa, f32x16& ob, int vb, bf16x8 pa0, bf16x8 pa1, bf16x8 pa2, bf16x8 pa3) {
;     ...
;   { const s16x4 al0 = tr_read<v_rd_off(DA, 0, 0)>(vb), ah0 = tr_read<v_rd_off(DA, 0, 1)>(vb), al1 = tr_read<v_rd_off(DA, 1, 0)>(vb), ah1 = tr_read<v_rd_off(DA, 1, 1)>(vb);
;     const s16x4 bl0 = tr_read<v_rd_off(DB, 0, 0)>(vb), bh0 = tr_read<v_rd_off(DB, 0, 1)>(vb), bl1 = tr_read<v_rd_off(DB, 1, 0)>(vb), bh1 = tr_read<v_rd_off(DB, 1, 1)>(vb);
;     asm volatile("s_waitcnt lgkmcnt(0)" ::: "memory"); SBAR();
;     oa = __builtin_amdgcn_mfma_f32_32x32x16_bf16(pa0, PK(al0, ah0), oa, 0, 0, 0); ob = __builtin_amdgcn_mfma_f32_32x32x16_bf16(pa0, PK(bl0, bh0), ob, 0, 0, 0);
;     oa = __builtin_amdgcn_mfma_f32_32x32x16_bf16(pa1, PK(al1, ah1), oa, 0, 0, 0); ob = __builtin_amdgcn_mfma_f32_32x32x16_bf16(pa1, PK(bl1, bh1), ob, 0, 0, 0); }
;   { const s16x4 al2 = tr_read<v_rd_off(DA, 2, 0)>(vb), ah2 = tr_read<v_rd_off(DA, 2, 1)>(vb), al3 = tr_read<v_rd_off(DA, 3, 0)>(vb), ah3 = tr_read<v_rd_off(DA, 3, 1)>(vb);
;     const s16x4 bl2 = tr_read<v_rd_off(DB, 2, 0)>(vb), bh2 = tr_read<v_rd_off(DB, 2, 1)>(vb), bl3 = tr_read<v_rd_off(DB, 3, 0)>(vb), bh3 = tr_read<v_rd_off(DB, 3, 1)>(vb);
;     asm volatile("s_waitcnt lgkmcnt(0)" ::: "memory"); SBAR();
;     oa = __builtin_amdgcn_mfma_f32_32x32x16_bf16(pa2, PK(al2, ah2), oa, 0, 0, 0); ob = __builtin_amdgcn_mfma_f32_32x32x16_bf16(pa2, PK(bl2, bh2), ob, 0, 0, 0);
;     oa = __builtin_amdgcn_mfma_f32_32x32x16_bf16(pa3, PK(al3, ah3), oa, 0, 0, 0); ob = __builtin_amdgcn_mfma_f32_32x32x16_bf16(pa3, PK(bl3, bh3), ob, 0, 0, 0); }
;     ...
; }
; __device__ __forceinline__ void pv_d0(f32x16* o, int vb, bf16x8 pa0, bf16x8 pa1, bf16x8 pa2, bf16x8 pa3) {
;   pv_pair<0, 1>(o[0], o[1], vb, pa0, pa1, pa2, pa3); pv_pair<2, 3>(o[2], o[3], vb, pa0, pa1, pa2, pa3);
	v_mfma_f32_32x32x16_bf16 v[0:15], v[220:223], v[224:227], v[0:15]
	ds_read_b64_tr_b16 v[224:225], v196 offset:0x2000
	ds_read_b64_tr_b16 v[226:227], v196 offset:0x2800
	s_waitcnt lgkmcnt(4)
	v_mfma_f32_32x32x16_bf16 v[48:63], v[220:223], v[232:235], v[48:63]
	v_mfma_f32_32x32x16_bf16 v[0:15], v[170:173], v[228:231], v[0:15]
	ds_read_b64_tr_b16 v[228:229], v196 offset:0x3000
	ds_read_b64_tr_b16 v[230:231], v196 offset:0x3800
	ds_read_b64_tr_b16 v[232:233], v196 offset:0x2200
	ds_read_b64_tr_b16 v[234:235], v196 offset:0x2a00
	ds_read_b64_tr_b16 v[240:241], v196 offset:0x3200
	ds_read_b64_tr_b16 v[242:243], v196 offset:0x3a00
	s_waitcnt lgkmcnt(8)
	v_mfma_f32_32x32x16_bf16 v[48:63], v[170:173], v[236:239], v[48:63]
	s_waitcnt lgkmcnt(6)
	v_mfma_f32_32x32x16_bf16 v[0:15], v[162:165], v[224:227], v[0:15]
	ds_read_b64_tr_b16 v[224:225], v196 offset:0x400
	ds_read_b64_tr_b16 v[226:227], v196 offset:0xc00
	s_waitcnt lgkmcnt(4)
	v_mfma_f32_32x32x16_bf16 v[48:63], v[162:165], v[232:235], v[48:63]
	v_mfma_f32_32x32x16_bf16 v[0:15], v[166:169], v[228:231], v[0:15]
	ds_read_b64_tr_b16 v[228:229], v196 offset:0x1400
	ds_read_b64_tr_b16 v[230:231], v196 offset:0x1c00
	ds_read_b64_tr_b16 v[232:233], v196 offset:0x600
	ds_read_b64_tr_b16 v[234:235], v196 offset:0xe00
	ds_read_b64_tr_b16 v[236:237], v196 offset:0x1600
	ds_read_b64_tr_b16 v[238:239], v196 offset:0x1e00
	s_waitcnt lgkmcnt(8)
	v_mfma_f32_32x32x16_bf16 v[48:63], v[166:169], v[240:243], v[48:63]
	s_waitcnt lgkmcnt(6)
	v_mfma_f32_32x32x16_bf16 v[32:47], v[220:223], v[224:227], v[32:47]
	s_waitcnt lgkmcnt(2)
	v_mfma_f32_32x32x16_bf16 v[16:31], v[220:223], v[232:235], v[16:31]
	ds_read_b64_tr_b16 v[220:221], v196 offset:0x2400
	ds_read_b64_tr_b16 v[222:223], v196 offset:0x2c00
	ds_read_b64_tr_b16 v[224:225], v196 offset:0x3400
	ds_read_b64_tr_b16 v[226:227], v196 offset:0x3c00
	v_mfma_f32_32x32x16_bf16 v[32:47], v[170:173], v[228:231], v[32:47]
	ds_read_b64_tr_b16 v[228:229], v196 offset:0x2600
	ds_read_b64_tr_b16 v[230:231], v196 offset:0x2e00
	ds_read_b64_tr_b16 v[232:233], v196 offset:0x3600
	ds_read_b64_tr_b16 v[234:235], v196 offset:0x3e00
	s_waitcnt lgkmcnt(8)
	v_mfma_f32_32x32x16_bf16 v[16:31], v[170:173], v[236:239], v[16:31]
	v_max_f32_e32 v161, v81, v81
	v_max_f32_e32 v170, v80, v80
	v_max_f32_e32 v161, v170, v161
	v_max3_f32 v161, v161, v82, v83
	v_max3_f32 v161, v161, v84, v85
	v_max3_f32 v161, v161, v86, v87
	v_max3_f32 v161, v161, v88, v89
	v_max3_f32 v161, v161, v90, v91
	v_max3_f32 v161, v161, v92, v93
	v_max3_f32 v161, v161, v94, v95
	v_max3_f32 v161, v161, v64, v65
	v_max3_f32 v161, v161, v66, v67
	v_max3_f32 v161, v161, v68, v69
	v_max3_f32 v161, v161, v70, v71
	v_max3_f32 v161, v161, v72, v73
	s_waitcnt lgkmcnt(6)
	v_mfma_f32_32x32x16_bf16 v[32:47], v[162:165], v[220:223], v[32:47]
	v_max3_f32 v161, v161, v74, v75
	v_max3_f32 v161, v161, v76, v77
	v_max3_f32 v161, v161, v78, v79
	s_waitcnt lgkmcnt(0)
	s_barrier
	s_waitcnt vmcnt(4)
	v_mfma_f32_32x32x16_bf16 v[16:31], v[162:165], v[228:231], v[16:31]
	v_mov_b32_e32 v162, v161
	s_nop 1
	v_permlane32_swap_b32_e32 v161, v162
	v_max_f32_e32 v162, v162, v162
	v_max_f32_e32 v161, v161, v161
	v_max_f32_e32 v161, v161, v162
	v_max_f32_e32 v163, v160, v160
	v_sub_f32_e32 v162, v161, v160
	v_max_f32_e32 v161, v163, v161
	v_mfma_f32_32x32x16_bf16 v[32:47], v[166:169], v[224:227], v[32:47]
	v_sub_f32_e32 v163, v160, v161
	v_mul_f32_e32 v163, 0x3e0293ee, v163
	v_exp_f32_e32 v163, v163
	v_cmp_ge_f32_e32 vcc, s67, v162
	s_cmp_eq_u64 vcc, exec
	s_cselect_b64 s[6:7], -1, 0
	v_cndmask_b32_e64 v219, v163, 1.0, s[6:7]
	v_mfma_f32_32x32x16_bf16 v[16:31], v[166:169], v[232:235], v[16:31]
	v_cmp_gt_f32_e32 vcc, 1.0, v219
	s_waitcnt vmcnt(4)
	ds_write_b128 v200, v[128:131]
	ds_write_b128 v201, v[132:135]
	ds_write_b128 v202, v[136:139] offset:32768
	ds_write_b128 v203, v[140:143] offset:32768
	s_cbranch_vccz .LBB0_448
	s_and_saveexec_b64 s[20:21], s[4:5]
	ds_write_b32 v198, v219 offset:128
	s_or_b64 exec, exec, s[20:21]
	s_waitcnt lgkmcnt(0)
	v_add_u32_e32 v174, v195, v197
	ds_read_b128 v[162:165], v174 offset:224
	ds_read_b128 v[166:169], v174 offset:192
	ds_read_b128 v[170:173], v174 offset:160
	ds_read_b128 v[220:223], v174 offset:128
	s_waitcnt lgkmcnt(3)
	v_pk_mul_f32 v[12:13], v[12:13], v[162:163]
	s_waitcnt lgkmcnt(2)
	v_pk_mul_f32 v[8:9], v[8:9], v[166:167]
	s_waitcnt lgkmcnt(1)
	v_pk_mul_f32 v[4:5], v[4:5], v[170:171]
	v_pk_mul_f32 v[14:15], v[14:15], v[164:165]
	v_pk_mul_f32 v[10:11], v[10:11], v[168:169]
	v_pk_mul_f32 v[6:7], v[6:7], v[172:173]
	s_waitcnt lgkmcnt(0)
	v_pk_mul_f32 v[2:3], v[2:3], v[222:223]
	v_pk_mul_f32 v[0:1], v[0:1], v[220:221]
	v_pk_mul_f32 v[60:61], v[60:61], v[162:163]
	v_pk_mul_f32 v[56:57], v[56:57], v[166:167]
	v_pk_mul_f32 v[52:53], v[52:53], v[170:171]
	v_pk_mul_f32 v[62:63], v[62:63], v[164:165]
	v_pk_mul_f32 v[58:59], v[58:59], v[168:169]
	v_pk_mul_f32 v[54:55], v[54:55], v[172:173]
	v_pk_mul_f32 v[50:51], v[50:51], v[222:223]
	v_pk_mul_f32 v[48:49], v[48:49], v[220:221]
	v_pk_mul_f32 v[44:45], v[44:45], v[162:163]
	v_pk_mul_f32 v[40:41], v[40:41], v[166:167]
	v_pk_mul_f32 v[36:37], v[36:37], v[170:171]
	v_pk_mul_f32 v[46:47], v[46:47], v[164:165]
	v_pk_mul_f32 v[42:43], v[42:43], v[168:169]
	v_pk_mul_f32 v[38:39], v[38:39], v[172:173]
	v_pk_mul_f32 v[34:35], v[34:35], v[222:223]
	v_pk_mul_f32 v[32:33], v[32:33], v[220:221]
	v_pk_mul_f32 v[28:29], v[28:29], v[162:163]
	v_pk_mul_f32 v[24:25], v[24:25], v[166:167]
	v_pk_mul_f32 v[20:21], v[20:21], v[170:171]
	v_pk_mul_f32 v[30:31], v[30:31], v[164:165]
	v_pk_mul_f32 v[26:27], v[26:27], v[168:169]
	v_pk_mul_f32 v[22:23], v[22:23], v[172:173]
	v_pk_mul_f32 v[18:19], v[18:19], v[222:223]
	v_pk_mul_f32 v[16:17], v[16:17], v[220:221]

; __device__ __forceinline__ void partialSM(f32x16& p0, f32x16& p1, float& m_reg, float& mn, float& alpha) {
;   constexpr float C = SCALE * 1.4426950408889634f;
;   float pmax = p0[0];
; #pragma unroll
;   for (int r = 1; r < 16; ++r) pmax = fmaxf(pmax, p0[r]);
; #pragma unroll
;   for (int r = 0; r < 16; ++r) pmax = fmaxf(pmax, p1[r]);
;   { auto rr = __builtin_amdgcn_permlane32_swap(__float_as_uint(pmax), __float_as_uint(pmax), false, false);
;     pmax = fmaxf(__uint_as_float(rr[0]), __uint_as_float(rr[1])); }
; template <int DA, int DB> __device__ __forceinline__ void pv_pair(f32x16& oa, f32x16& ob, int vb, bf16x8 pa0, bf16x8 pa1, bf16x8 pa2, bf16x8 pa3) {
;     ...
;   { const s16x4 al0 = tr_read<v_rd_off(DA, 0, 0)>(vb), ah0 = tr_read<v_rd_off(DA, 0, 1)>(vb), al1 = tr_read<v_rd_off(DA, 1, 0)>(vb), ah1 = tr_read<v_rd_off(DA, 1, 1)>(vb);
;     const s16x4 bl0 = tr_read<v_rd_off(DB, 0, 0)>(vb), bh0 = tr_read<v_rd_off(DB, 0, 1)>(vb), bl1 = tr_read<v_rd_off(DB, 1, 0)>(vb), bh1 = tr_read<v_rd_off(DB, 1, 1)>(vb);
;     asm volatile("s_waitcnt lgkmcnt(0)" ::: "memory"); SBAR();
;     oa = __builtin_amdgcn_mfma_f32_32x32x16_bf16(pa0, PK(al0, ah0), oa, 0, 0, 0); ob = __builtin_amdgcn_mfma_f32_32x32x16_bf16(pa0, PK(bl0, bh0), ob, 0, 0, 0);
;     oa = __builtin_amdgcn_mfma_f32_32x32x16_bf16(pa1, PK(al1, ah1), oa, 0, 0, 0); ob = __builtin_amdgcn_mfma_f32_32x32x16_bf16(pa1, PK(bl1, bh1), ob, 0, 0, 0); }
;   { const s16x4 al2 = tr_read<v_rd_off(DA, 2, 0)>(vb), ah2 = tr_read<v_rd_off(DA, 2, 1)>(vb), al3 = tr_read<v_rd_off(DA, 3, 0)>(vb), ah3 = tr_read<v_rd_off(DA, 3, 1)>(vb);
;     const s16x4 bl2 = tr_read<v_rd_off(DB, 2, 0)>(vb), bh2 = tr_read<v_rd_off(DB, 2, 1)>(vb), bl3 = tr_read<v_rd_off(DB, 3, 0)>(vb), bh3 = tr_read<v_rd_off(DB, 3, 1)>(vb);
;     asm volatile("s_waitcnt lgkmcnt(0)" ::: "memory"); SBAR();
;     oa = __builtin_amdgcn_mfma_f32_32x32x16_bf16(pa2, PK(al2, ah2), oa, 0, 0, 0); ob = __builtin_amdgcn_mfma_f32_32x32x16_bf16(pa2, PK(bl2, bh2), ob, 0, 0, 0);
;     oa = __builtin_amdgcn_mfma_f32_32x32x16_bf16(pa3, PK(al3, ah3), oa, 0, 0, 0); ob = __builtin_amdgcn_mfma_f32_32x32x16_bf16(pa3, PK(bl3, bh3), ob, 0, 0, 0); }
;     ...
; }
; __device__ __forceinline__ void pv_d0(f32x16* o, int vb, bf16x8 pa0, bf16x8 pa1, bf16x8 pa2, bf16x8 pa3) {
;   pv_pair<0, 1>(o[0], o[1], vb, pa0, pa1, pa2, pa3); pv_pair<2, 3>(o[2], o[3], vb, pa0, pa1, pa2, pa3);
.LBB0_450:
	ds_read_b64_tr_b16 v[190:191], v199 offset:0
	ds_read_b64_tr_b16 v[192:193], v199 offset:0x800
	ds_read_b64_tr_b16 v[224:225], v199 offset:0x1000
	ds_read_b64_tr_b16 v[226:227], v199 offset:0x1800
	ds_read_b64_tr_b16 v[228:229], v199 offset:0x200
	ds_read_b64_tr_b16 v[230:231], v199 offset:0xa00
	ds_read_b64_tr_b16 v[232:233], v199 offset:0x1200
	ds_read_b64_tr_b16 v[234:235], v199 offset:0x1a00
	s_nop 0
	s_waitcnt lgkmcnt(6)
	v_mfma_f32_32x32x16_bf16 v[0:15], v[172:175], v[190:193], v[0:15]
	ds_read_b64_tr_b16 v[190:191], v199 offset:0x2000
	ds_read_b64_tr_b16 v[192:193], v199 offset:0x2800
	s_waitcnt lgkmcnt(4)
	v_mfma_f32_32x32x16_bf16 v[48:63], v[172:175], v[228:231], v[48:63]
	v_mfma_f32_32x32x16_bf16 v[0:15], v[168:171], v[224:227], v[0:15]
	ds_read_b64_tr_b16 v[224:225], v199 offset:0x3000
	ds_read_b64_tr_b16 v[226:227], v199 offset:0x3800
	ds_read_b64_tr_b16 v[228:229], v199 offset:0x2200
	ds_read_b64_tr_b16 v[230:231], v199 offset:0x2a00
	ds_read_b64_tr_b16 v[236:237], v199 offset:0x3200
	ds_read_b64_tr_b16 v[238:239], v199 offset:0x3a00
	s_waitcnt lgkmcnt(8)
	v_mfma_f32_32x32x16_bf16 v[48:63], v[168:171], v[232:235], v[48:63]
	s_waitcnt lgkmcnt(6)
	v_mfma_f32_32x32x16_bf16 v[0:15], v[164:167], v[190:193], v[0:15]
	ds_read_b64_tr_b16 v[190:191], v199 offset:0x400
	ds_read_b64_tr_b16 v[192:193], v199 offset:0xc00
	s_waitcnt lgkmcnt(4)
	v_mfma_f32_32x32x16_bf16 v[48:63], v[164:167], v[228:231], v[48:63]
	v_mfma_f32_32x32x16_bf16 v[0:15], v[160:163], v[224:227], v[0:15]
	ds_read_b64_tr_b16 v[224:225], v199 offset:0x1400
	ds_read_b64_tr_b16 v[226:227], v199 offset:0x1c00
	ds_read_b64_tr_b16 v[228:229], v199 offset:0x600
	ds_read_b64_tr_b16 v[230:231], v199 offset:0xe00
	ds_read_b64_tr_b16 v[232:233], v199 offset:0x1600
	ds_read_b64_tr_b16 v[234:235], v199 offset:0x1e00
	s_waitcnt lgkmcnt(8)
	v_mfma_f32_32x32x16_bf16 v[48:63], v[160:163], v[236:239], v[48:63]
	s_waitcnt lgkmcnt(6)
	v_mfma_f32_32x32x16_bf16 v[32:47], v[172:175], v[190:193], v[32:47]
	s_waitcnt lgkmcnt(2)
	v_mfma_f32_32x32x16_bf16 v[16:31], v[172:175], v[228:231], v[16:31]
	ds_read_b64_tr_b16 v[172:173], v199 offset:0x2400
	ds_read_b64_tr_b16 v[174:175], v199 offset:0x2c00
	ds_read_b64_tr_b16 v[190:191], v199 offset:0x3400
	ds_read_b64_tr_b16 v[192:193], v199 offset:0x3c00
	v_mfma_f32_32x32x16_bf16 v[32:47], v[168:171], v[224:227], v[32:47]
	ds_read_b64_tr_b16 v[224:225], v199 offset:0x2600
	ds_read_b64_tr_b16 v[226:227], v199 offset:0x2e00
	ds_read_b64_tr_b16 v[228:229], v199 offset:0x3600
	ds_read_b64_tr_b16 v[230:231], v199 offset:0x3e00
	s_waitcnt lgkmcnt(8)
	v_mfma_f32_32x32x16_bf16 v[16:31], v[168:171], v[232:235], v[16:31]
	v_max_f32_e32 v168, v81, v81
	v_max_f32_e32 v169, v80, v80
	v_max_f32_e32 v168, v169, v168
	v_max3_f32 v168, v168, v82, v83
	v_max3_f32 v168, v168, v84, v85
	v_max3_f32 v168, v168, v86, v87
	v_max3_f32 v168, v168, v88, v89
	v_max3_f32 v168, v168, v90, v91
	v_max3_f32 v168, v168, v92, v93
	v_max3_f32 v168, v168, v94, v95
	v_max3_f32 v168, v168, v64, v65
	v_max3_f32 v168, v168, v66, v67
	s_waitcnt lgkmcnt(6)
	v_mfma_f32_32x32x16_bf16 v[32:47], v[164:167], v[172:175], v[32:47]
	s_waitcnt lgkmcnt(0)
	s_barrier
	s_waitcnt vmcnt(4)
	s_waitcnt vmcnt(3)
	ds_write_b128 v200, v[144:147] offset:16384
	s_waitcnt vmcnt(2)
	ds_write_b128 v201, v[148:151] offset:16384
	s_waitcnt vmcnt(1)
	ds_write_b128 v202, v[152:155] offset:49152
	s_waitcnt vmcnt(0)
	ds_write_b128 v203, v[156:159] offset:49152
	v_mfma_f32_32x32x16_bf16 v[16:31], v[164:167], v[224:227], v[16:31]
	v_max3_f32 v164, v168, v68, v69
	v_max3_f32 v164, v164, v70, v71
	v_max3_f32 v164, v164, v72, v73
	v_max3_f32 v164, v164, v74, v75
	v_max3_f32 v164, v164, v76, v77
	v_max3_f32 v164, v164, v78, v79
	v_mov_b32_e32 v165, v164
	s_nop 1
	v_permlane32_swap_b32_e32 v164, v165
	v_max_f32_e32 v165, v165, v165
	v_max_f32_e32 v164, v164, v164
	v_max_f32_e32 v164, v164, v165
	v_max_f32_e32 v166, v220, v220
	v_sub_f32_e32 v165, v164, v220
	v_max_f32_e32 v164, v166, v164
	v_mfma_f32_32x32x16_bf16 v[32:47], v[160:163], v[190:193], v[32:47]
	v_cmp_ge_f32_e32 vcc, s67, v165
	s_cmp_eq_u64 vcc, exec
	s_cselect_b64 s[6:7], -1, 0
	v_mfma_f32_32x32x16_bf16 v[16:31], v[160:163], v[228:231], v[16:31]
	v_sub_f32_e32 v160, v220, v164
	v_mul_f32_e32 v160, 0x3e0293ee, v160
	v_exp_f32_e32 v160, v160
	s_nop 0
	v_cndmask_b32_e64 v161, v160, 1.0, s[6:7]
	v_cmp_gt_f32_e32 vcc, 1.0, v161
	s_cbranch_vccz .LBB0_454
	s_and_saveexec_b64 s[22:23], s[4:5]
	ds_write_b32 v198, v161 offset:128
	s_or_b64 exec, exec, s[22:23]
	s_waitcnt lgkmcnt(0)
	v_add_u32_e32 v156, v195, v197
	ds_read_b128 v[144:147], v156 offset:224
	ds_read_b128 v[148:151], v156 offset:192
	ds_read_b128 v[152:155], v156 offset:160
	ds_read_b128 v[156:159], v156 offset:128
	s_waitcnt lgkmcnt(3)
	v_pk_mul_f32 v[12:13], v[12:13], v[144:145]
	s_waitcnt lgkmcnt(2)
	v_pk_mul_f32 v[8:9], v[8:9], v[148:149]
	s_waitcnt lgkmcnt(1)
	v_pk_mul_f32 v[4:5], v[4:5], v[152:153]
	v_pk_mul_f32 v[14:15], v[14:15], v[146:147]
	v_pk_mul_f32 v[10:11], v[10:11], v[150:151]
	v_pk_mul_f32 v[6:7], v[6:7], v[154:155]
	s_waitcnt lgkmcnt(0)
	v_pk_mul_f32 v[2:3], v[2:3], v[158:159]
	v_pk_mul_f32 v[0:1], v[0:1], v[156:157]
	v_pk_mul_f32 v[60:61], v[60:61], v[144:145]
	v_pk_mul_f32 v[56:57], v[56:57], v[148:149]
	v_pk_mul_f32 v[52:53], v[52:53], v[152:153]
	v_pk_mul_f32 v[62:63], v[62:63], v[146:147]
	v_pk_mul_f32 v[58:59], v[58:59], v[150:151]
	v_pk_mul_f32 v[54:55], v[54:55], v[154:155]
	v_pk_mul_f32 v[50:51], v[50:51], v[158:159]
	v_pk_mul_f32 v[48:49], v[48:49], v[156:157]
	v_pk_mul_f32 v[44:45], v[44:45], v[144:145]
	v_pk_mul_f32 v[40:41], v[40:41], v[148:149]
	v_pk_mul_f32 v[36:37], v[36:37], v[152:153]
	v_pk_mul_f32 v[46:47], v[46:47], v[146:147]
	v_pk_mul_f32 v[42:43], v[42:43], v[150:151]
	v_pk_mul_f32 v[38:39], v[38:39], v[154:155]
	v_pk_mul_f32 v[34:35], v[34:35], v[158:159]
	v_pk_mul_f32 v[32:33], v[32:33], v[156:157]
	v_pk_mul_f32 v[28:29], v[28:29], v[144:145]
	v_pk_mul_f32 v[24:25], v[24:25], v[148:149]
	v_pk_mul_f32 v[20:21], v[20:21], v[152:153]
	v_pk_mul_f32 v[30:31], v[30:31], v[146:147]
	v_pk_mul_f32 v[26:27], v[26:27], v[150:151]
	v_pk_mul_f32 v[22:23], v[22:23], v[154:155]
	v_pk_mul_f32 v[18:19], v[18:19], v[158:159]
	v_pk_mul_f32 v[16:17], v[16:17], v[156:157]

; #define SBAR() __builtin_amdgcn_sched_barrier(0)
; __device__ __forceinline__ void finishSM(f32x16& p0, f32x16& p1, float alpha, float& l_reg, bf16x8& pa0, bf16x8& pa1, bf16x8& pa2, bf16x8& pa3) {
; #pragma unroll
;   for (int r = 0; r < 16; ++r) p1[r] = __builtin_amdgcn_exp2f(p1[r]);
;   float ps = 0;
; #pragma unroll
;   for (int r = 0; r < 16; ++r) ps += p0[r];
; #pragma unroll
;   for (int r = 0; r < 16; ++r) ps += p1[r];
;   { auto rr = __builtin_amdgcn_permlane32_swap(__float_as_uint(ps), __float_as_uint(ps), false, false);
;     ps = __uint_as_float(rr[0]) + __uint_as_float(rr[1]); }
;   l_reg = l_reg * alpha + ps;
;     ...
;   PK4(p0, 0, pa0); PK4(p0, 8, pa1); PK4(p1, 0, pa2); PK4(p1, 8, pa3);
;     ...
; }
; __device__ __forceinline__ void qkt(f32x16& p0, f32x16& p1, const bf16_t* Ks, const bf16x8* qr, int r32, int hi) {
;   p0 = f32x16{}; p1 = f32x16{};
; #pragma unroll
;   for (int d0 = 0; d0 < 8; ++d0) { int cb = (d0 * 16 + hi * 8) * 2;
;     bf16x8 b0 = *reinterpret_cast<const bf16x8*>((const char*)Ks + KSWZ(r32, cb));
;     bf16x8 b1 = *reinterpret_cast<const bf16x8*>((const char*)Ks + KSWZ(32 + r32, cb));
;     p0 = __builtin_amdgcn_mfma_f32_32x32x16_bf16(b0, qr[d0], p0, 0, 0, 0);
;     p1 = __builtin_amdgcn_mfma_f32_32x32x16_bf16(b1, qr[d0], p1, 0, 0, 0); }
; template <int D0> __device__ __forceinline__ void pv_one(f32x16& od, int vb, bf16x8 pa0, bf16x8 pa1, bf16x8 pa2, bf16x8 pa3) {
;   const s16x4 l0 = tr_read<v_rd_off(D0, 0, 0)>(vb), h0 = tr_read<v_rd_off(D0, 0, 1)>(vb), l1 = tr_read<v_rd_off(D0, 1, 0)>(vb), h1 = tr_read<v_rd_off(D0, 1, 1)>(vb);
;   const s16x4 l2 = tr_read<v_rd_off(D0, 2, 0)>(vb), h2 = tr_read<v_rd_off(D0, 2, 1)>(vb), l3 = tr_read<v_rd_off(D0, 3, 0)>(vb), h3 = tr_read<v_rd_off(D0, 3, 1)>(vb);
;   asm volatile("s_waitcnt lgkmcnt(0)" ::: "memory"); SBAR();
.LBB0_1524:
	ds_read_b128 v[64:67], v204 offset:49152
	ds_read_b128 v[68:71], v204 offset:57344
	ds_read_b128 v[218:221], v205 offset:49152
	ds_read_b128 v[222:225], v205 offset:57344
	ds_read_b128 v[248:251], v206 offset:49152
	ds_read_b128 v[252:255], v206 offset:57344
	v_add_f32_e32 v161, 0, v175
	v_add_f32_e32 v161, v191, v161
	s_waitcnt lgkmcnt(5)
	v_mfma_f32_32x32x16_bf16 v[80:95], v[64:67], v[124:127], 0
	v_add_f32_e32 v161, v173, v161
	v_add_f32_e32 v161, v190, v161
	v_add_f32_e32 v161, v172, v161
	v_add_f32_e32 v161, v174, v161
	v_add_f32_e32 v161, v170, v161
	v_add_f32_e32 v161, v171, v161
	v_add_f32_e32 v161, v167, v161
	s_waitcnt lgkmcnt(4)
	v_mfma_f32_32x32x16_bf16 v[64:79], v[68:71], v[124:127], 0
	v_add_f32_e32 v161, v169, v161
	v_add_f32_e32 v161, v166, v161
	v_add_f32_e32 v161, v168, v161
	v_exp_f32_e32 v156, v156
	v_add_f32_e32 v161, v163, v161
	v_exp_f32_e32 v157, v157
	v_add_f32_e32 v161, v164, v161
	s_waitcnt lgkmcnt(3)
	v_mfma_f32_32x32x16_bf16 v[80:95], v[218:221], v[120:123], v[80:95]
	v_exp_f32_e32 v154, v154
	v_add_f32_e32 v161, v162, v161
	v_exp_f32_e32 v155, v155
	v_add_f32_e32 v161, v165, v161
	v_exp_f32_e32 v150, v150
	v_add_f32_e32 v161, v156, v161
	v_exp_f32_e32 v151, v151
	s_waitcnt lgkmcnt(2)
	v_mfma_f32_32x32x16_bf16 v[64:79], v[222:225], v[120:123], v[64:79]
	ds_read_b128 v[218:221], v207 offset:49152
	ds_read_b128 v[222:225], v207 offset:57344
	v_add_f32_e32 v161, v157, v161
	v_exp_f32_e32 v148, v148
	v_add_f32_e32 v161, v154, v161
	v_exp_f32_e32 v149, v149
	v_add_f32_e32 v161, v155, v161
	v_exp_f32_e32 v144, v144
	s_waitcnt lgkmcnt(3)
	v_mfma_f32_32x32x16_bf16 v[80:95], v[248:251], v[116:119], v[80:95]
	v_add_f32_e32 v161, v150, v161
	v_exp_f32_e32 v145, v145
	v_add_f32_e32 v161, v151, v161
	v_exp_f32_e32 v158, v158
	v_add_f32_e32 v161, v148, v161
	v_exp_f32_e32 v159, v159
	v_add_f32_e32 v161, v149, v161
	s_waitcnt lgkmcnt(2)
	v_mfma_f32_32x32x16_bf16 v[64:79], v[252:255], v[116:119], v[64:79]
	ds_read_b128 v[248:251], v208 offset:49152
	ds_read_b128 v[252:255], v208 offset:57344
	v_exp_f32_e32 v152, v152
	v_add_f32_e32 v161, v144, v161
	v_exp_f32_e32 v153, v153
	v_add_f32_e32 v161, v145, v161
	v_exp_f32_e32 v146, v146
	v_add_f32_e32 v161, v158, v161
	s_waitcnt lgkmcnt(3)
	v_mfma_f32_32x32x16_bf16 v[80:95], v[218:221], v[112:115], v[80:95]
	v_exp_f32_e32 v147, v147
	v_add_f32_e32 v161, v159, v161
	v_add_f32_e32 v161, v152, v161
	v_add_f32_e32 v161, v153, v161
	v_add_f32_e32 v161, v146, v161
	v_add_f32_e32 v215, v147, v161
	s_waitcnt lgkmcnt(2)
	v_mfma_f32_32x32x16_bf16 v[64:79], v[222:225], v[112:115], v[64:79]
	ds_read_b128 v[218:221], v209 offset:49152
	ds_read_b128 v[222:225], v209 offset:57344
	s_waitcnt lgkmcnt(3)
	v_mfma_f32_32x32x16_bf16 v[80:95], v[248:251], v[108:111], v[80:95]
	s_waitcnt lgkmcnt(2)
	v_mfma_f32_32x32x16_bf16 v[64:79], v[252:255], v[108:111], v[64:79]
	ds_read_b128 v[248:251], v210 offset:49152
	ds_read_b128 v[252:255], v210 offset:57344
	s_waitcnt lgkmcnt(3)
	v_mfma_f32_32x32x16_bf16 v[80:95], v[218:221], v[104:107], v[80:95]
	s_waitcnt lgkmcnt(2)
	v_mfma_f32_32x32x16_bf16 v[64:79], v[222:225], v[104:107], v[64:79]
	ds_read_b128 v[218:221], v211 offset:49152
	ds_read_b128 v[222:225], v211 offset:57344
	s_waitcnt lgkmcnt(3)
	v_mfma_f32_32x32x16_bf16 v[80:95], v[248:251], v[100:103], v[80:95]
	s_waitcnt lgkmcnt(2)
	v_mfma_f32_32x32x16_bf16 v[64:79], v[252:255], v[100:103], v[64:79]
	s_waitcnt lgkmcnt(1)
	v_mfma_f32_32x32x16_bf16 v[80:95], v[218:221], v[96:99], v[80:95]
	v_mov_b32_e32 v218, v215
	s_nop 1
	v_permlane32_swap_b32_e32 v215, v218
	v_cvt_pk_bf16_f32 v220, v175, v191
	v_cvt_pk_bf16_f32 v221, v173, v190
	s_waitcnt lgkmcnt(0)
	v_mfma_f32_32x32x16_bf16 v[64:79], v[222:225], v[96:99], v[64:79]
	v_cvt_pk_bf16_f32 v222, v172, v174
	v_cvt_pk_bf16_f32 v223, v170, v171
	v_cvt_pk_bf16_f32 v170, v167, v169
	v_cvt_pk_bf16_f32 v171, v166, v168
	v_cvt_pk_bf16_f32 v172, v163, v164
	v_cvt_pk_bf16_f32 v173, v162, v165
	v_cvt_pk_bf16_f32 v162, v156, v157
	v_cvt_pk_bf16_f32 v163, v154, v155
	v_cvt_pk_bf16_f32 v164, v150, v151
	v_cvt_pk_bf16_f32 v165, v148, v149
	v_cvt_pk_bf16_f32 v166, v144, v145
	v_cvt_pk_bf16_f32 v167, v158, v159
	v_cvt_pk_bf16_f32 v168, v152, v153
	v_cvt_pk_bf16_f32 v169, v146, v147
	s_nop 0
	v_permlane32_swap_b32_e32 v220, v222
	v_permlane32_swap_b32_e32 v221, v223
	v_permlane32_swap_b32_e32 v170, v172
	v_permlane32_swap_b32_e32 v171, v173
	v_permlane32_swap_b32_e32 v162, v164
	v_permlane32_swap_b32_e32 v163, v165
	v_permlane32_swap_b32_e32 v166, v168
	v_permlane32_swap_b32_e32 v167, v169
	v_lshl_add_u64 v[192:193], s[18:19], 0, v[180:181]
	v_add_co_u32_e32 v144, vcc, s63, v192
	v_lshl_add_u64 v[190:191], s[18:19], 0, v[182:183]
	s_nop 0
	v_addc_co_u32_e32 v145, vcc, 0, v193, vcc
	v_add_co_u32_e32 v148, vcc, s63, v190
	s_nop 1
	v_addc_co_u32_e32 v149, vcc, 0, v191, vcc
	v_add_co_u32_e32 v152, vcc, s64, v192
	global_load_dwordx4 v[144:147], v[144:145], off
	s_nop 0
	global_load_dwordx4 v[148:151], v[148:149], off
	v_addc_co_u32_e32 v153, vcc, 0, v193, vcc
	v_add_co_u32_e32 v156, vcc, s64, v190
	s_nop 1
	v_addc_co_u32_e32 v157, vcc, 0, v191, vcc
	global_load_dwordx4 v[152:155], v[152:153], off
	s_nop 0
	global_load_dwordx4 v[156:159], v[156:157], off
	ds_read_b64_tr_b16 v[224:225], v196 offset:0
	ds_read_b64_tr_b16 v[226:227], v196 offset:0x800
	ds_read_b64_tr_b16 v[228:229], v196 offset:0x1000
	ds_read_b64_tr_b16 v[230:231], v196 offset:0x1800
	ds_read_b64_tr_b16 v[232:233], v196 offset:0x200
	ds_read_b64_tr_b16 v[234:235], v196 offset:0xa00
	ds_read_b64_tr_b16 v[236:237], v196 offset:0x1200
	ds_read_b64_tr_b16 v[238:239], v196 offset:0x1a00
	s_nop 0
	s_waitcnt lgkmcnt(6)
; __device__ __forceinline__ void partialSM(f32x16& p0, f32x16& p1, float& m_reg, float& mn, float& alpha) {
;   constexpr float C = SCALE * 1.4426950408889634f;
;   float pmax = p0[0];
; #pragma unroll
;   for (int r = 1; r < 16; ++r) pmax = fmaxf(pmax, p0[r]);
; #pragma unroll
;   for (int r = 0; r < 16; ++r) pmax = fmaxf(pmax, p1[r]);
;   { auto rr = __builtin_amdgcn_permlane32_swap(__float_as_uint(pmax), __float_as_uint(pmax), false, false);
;     pmax = fmaxf(__uint_as_float(rr[0]), __uint_as_float(rr[1])); }
; template <int DA, int DB> __device__ __forceinline__ void pv_pair(f32x16& oa, f32x16& ob, int vb, bf16x8 pa0, bf16x8 pa1, bf16x8 pa2, bf16x8 pa3) {
;     ...
;   { const s16x4 al0 = tr_read<v_rd_off(DA, 0, 0)>(vb), ah0 = tr_read<v_rd_off(DA, 0, 1)>(vb), al1 = tr_read<v_rd_off(DA, 1, 0)>(vb), ah1 = tr_read<v_rd_off(DA, 1, 1)>(vb);
;     const s16x4 bl0 = tr_read<v_rd_off(DB, 0, 0)>(vb), bh0 = tr_read<v_rd_off(DB, 0, 1)>(vb), bl1 = tr_read<v_rd_off(DB, 1, 0)>(vb), bh1 = tr_read<v_rd_off(DB, 1, 1)>(vb);
;     asm volatile("s_waitcnt lgkmcnt(0)" ::: "memory"); SBAR();
;     oa = __builtin_amdgcn_mfma_f32_32x32x16_bf16(pa0, PK(al0, ah0), oa, 0, 0, 0); ob = __builtin_amdgcn_mfma_f32_32x32x16_bf16(pa0, PK(bl0, bh0), ob, 0, 0, 0);
;     oa = __builtin_amdgcn_mfma_f32_32x32x16_bf16(pa1, PK(al1, ah1), oa, 0, 0, 0); ob = __builtin_amdgcn_mfma_f32_32x32x16_bf16(pa1, PK(bl1, bh1), ob, 0, 0, 0); }
;   { const s16x4 al2 = tr_read<v_rd_off(DA, 2, 0)>(vb), ah2 = tr_read<v_rd_off(DA, 2, 1)>(vb), al3 = tr_read<v_rd_off(DA, 3, 0)>(vb), ah3 = tr_read<v_rd_off(DA, 3, 1)>(vb);
;     const s16x4 bl2 = tr_read<v_rd_off(DB, 2, 0)>(vb), bh2 = tr_read<v_rd_off(DB, 2, 1)>(vb), bl3 = tr_read<v_rd_off(DB, 3, 0)>(vb), bh3 = tr_read<v_rd_off(DB, 3, 1)>(vb);
;     asm volatile("s_waitcnt lgkmcnt(0)" ::: "memory"); SBAR();
;     oa = __builtin_amdgcn_mfma_f32_32x32x16_bf16(pa2, PK(al2, ah2), oa, 0, 0, 0); ob = __builtin_amdgcn_mfma_f32_32x32x16_bf16(pa2, PK(bl2, bh2), ob, 0, 0, 0);
;     oa = __builtin_amdgcn_mfma_f32_32x32x16_bf16(pa3, PK(al3, ah3), oa, 0, 0, 0); ob = __builtin_amdgcn_mfma_f32_32x32x16_bf16(pa3, PK(bl3, bh3), ob, 0, 0, 0); }
;     ...
; }
; __device__ __forceinline__ void pv_d0(f32x16* o, int vb, bf16x8 pa0, bf16x8 pa1, bf16x8 pa2, bf16x8 pa3) {
;   pv_pair<0, 1>(o[0], o[1], vb, pa0, pa1, pa2, pa3); pv_pair<2, 3>(o[2], o[3], vb, pa0, pa1, pa2, pa3);
	v_mfma_f32_32x32x16_bf16 v[0:15], v[220:223], v[224:227], v[0:15]
	ds_read_b64_tr_b16 v[224:225], v196 offset:0x2000
	ds_read_b64_tr_b16 v[226:227], v196 offset:0x2800
	s_waitcnt lgkmcnt(4)
	v_mfma_f32_32x32x16_bf16 v[48:63], v[220:223], v[232:235], v[48:63]
	v_mfma_f32_32x32x16_bf16 v[0:15], v[170:173], v[228:231], v[0:15]
	ds_read_b64_tr_b16 v[228:229], v196 offset:0x3000
	ds_read_b64_tr_b16 v[230:231], v196 offset:0x3800
	ds_read_b64_tr_b16 v[232:233], v196 offset:0x2200
	ds_read_b64_tr_b16 v[234:235], v196 offset:0x2a00
	ds_read_b64_tr_b16 v[240:241], v196 offset:0x3200
	ds_read_b64_tr_b16 v[242:243], v196 offset:0x3a00
	s_waitcnt lgkmcnt(8)
	v_mfma_f32_32x32x16_bf16 v[48:63], v[170:173], v[236:239], v[48:63]
	s_waitcnt lgkmcnt(6)
	v_mfma_f32_32x32x16_bf16 v[0:15], v[162:165], v[224:227], v[0:15]
	ds_read_b64_tr_b16 v[224:225], v196 offset:0x400
	ds_read_b64_tr_b16 v[226:227], v196 offset:0xc00
	s_waitcnt lgkmcnt(4)
	v_mfma_f32_32x32x16_bf16 v[48:63], v[162:165], v[232:235], v[48:63]
	v_mfma_f32_32x32x16_bf16 v[0:15], v[166:169], v[228:231], v[0:15]
	ds_read_b64_tr_b16 v[228:229], v196 offset:0x1400
	ds_read_b64_tr_b16 v[230:231], v196 offset:0x1c00
	ds_read_b64_tr_b16 v[232:233], v196 offset:0x600
	ds_read_b64_tr_b16 v[234:235], v196 offset:0xe00
	ds_read_b64_tr_b16 v[236:237], v196 offset:0x1600
	ds_read_b64_tr_b16 v[238:239], v196 offset:0x1e00
	s_waitcnt lgkmcnt(8)
	v_mfma_f32_32x32x16_bf16 v[48:63], v[166:169], v[240:243], v[48:63]
	s_waitcnt lgkmcnt(6)
	v_mfma_f32_32x32x16_bf16 v[32:47], v[220:223], v[224:227], v[32:47]
	s_waitcnt lgkmcnt(2)
	v_mfma_f32_32x32x16_bf16 v[16:31], v[220:223], v[232:235], v[16:31]
	ds_read_b64_tr_b16 v[220:221], v196 offset:0x2400
	ds_read_b64_tr_b16 v[222:223], v196 offset:0x2c00
	ds_read_b64_tr_b16 v[224:225], v196 offset:0x3400
	ds_read_b64_tr_b16 v[226:227], v196 offset:0x3c00
	v_mfma_f32_32x32x16_bf16 v[32:47], v[170:173], v[228:231], v[32:47]
	ds_read_b64_tr_b16 v[228:229], v196 offset:0x2600
	ds_read_b64_tr_b16 v[230:231], v196 offset:0x2e00
	ds_read_b64_tr_b16 v[232:233], v196 offset:0x3600
	ds_read_b64_tr_b16 v[234:235], v196 offset:0x3e00
	s_waitcnt lgkmcnt(8)
	v_mfma_f32_32x32x16_bf16 v[16:31], v[170:173], v[236:239], v[16:31]
	v_max_f32_e32 v161, v81, v81
	v_max_f32_e32 v170, v80, v80
	v_max_f32_e32 v161, v170, v161
	v_max3_f32 v161, v161, v82, v83
	v_max3_f32 v161, v161, v84, v85
	v_max3_f32 v161, v161, v86, v87
	v_max3_f32 v161, v161, v88, v89
	v_max3_f32 v161, v161, v90, v91
	v_max3_f32 v161, v161, v92, v93
	v_max3_f32 v161, v161, v94, v95
	v_max3_f32 v161, v161, v64, v65
	v_max3_f32 v161, v161, v66, v67
	v_max3_f32 v161, v161, v68, v69
	v_max3_f32 v161, v161, v70, v71
	v_max3_f32 v161, v161, v72, v73
	s_waitcnt lgkmcnt(6)
	v_mfma_f32_32x32x16_bf16 v[32:47], v[162:165], v[220:223], v[32:47]
	v_max3_f32 v161, v161, v74, v75
	v_max3_f32 v161, v161, v76, v77
	v_max3_f32 v161, v161, v78, v79
	s_waitcnt lgkmcnt(0)
	s_barrier
	s_waitcnt vmcnt(4)
	v_mfma_f32_32x32x16_bf16 v[16:31], v[162:165], v[228:231], v[16:31]
	v_mov_b32_e32 v162, v161
	s_nop 1
	v_permlane32_swap_b32_e32 v161, v162
	v_max_f32_e32 v162, v162, v162
	v_max_f32_e32 v161, v161, v161
	v_max_f32_e32 v161, v161, v162
	v_max_f32_e32 v163, v160, v160
	v_sub_f32_e32 v162, v161, v160
	v_max_f32_e32 v161, v163, v161
	v_mfma_f32_32x32x16_bf16 v[32:47], v[166:169], v[224:227], v[32:47]
	v_sub_f32_e32 v163, v160, v161
	v_mul_f32_e32 v163, 0x3e0293ee, v163
	v_exp_f32_e32 v163, v163
	v_cmp_ge_f32_e32 vcc, s62, v162
	s_cmp_eq_u64 vcc, exec
	s_cselect_b64 s[6:7], -1, 0
	v_cndmask_b32_e64 v219, v163, 1.0, s[6:7]
	v_mfma_f32_32x32x16_bf16 v[16:31], v[166:169], v[232:235], v[16:31]
	v_cmp_gt_f32_e32 vcc, 1.0, v219
	s_waitcnt vmcnt(4)
	ds_write_b128 v200, v[128:131]
	ds_write_b128 v201, v[132:135]
	ds_write_b128 v202, v[136:139] offset:32768
	ds_write_b128 v203, v[140:143] offset:32768
	s_cbranch_vccz .LBB0_1528
	s_and_saveexec_b64 s[20:21], s[4:5]
	ds_write_b32 v198, v219 offset:128
	s_or_b64 exec, exec, s[20:21]
	s_waitcnt lgkmcnt(0)
	v_add_u32_e32 v174, v195, v197
	ds_read_b128 v[162:165], v174 offset:224
	ds_read_b128 v[166:169], v174 offset:192
	ds_read_b128 v[170:173], v174 offset:160
	ds_read_b128 v[220:223], v174 offset:128
	s_waitcnt lgkmcnt(3)
	v_pk_mul_f32 v[12:13], v[12:13], v[162:163]
	s_waitcnt lgkmcnt(2)
	v_pk_mul_f32 v[8:9], v[8:9], v[166:167]
	s_waitcnt lgkmcnt(1)
	v_pk_mul_f32 v[4:5], v[4:5], v[170:171]
	v_pk_mul_f32 v[14:15], v[14:15], v[164:165]
	v_pk_mul_f32 v[10:11], v[10:11], v[168:169]
	v_pk_mul_f32 v[6:7], v[6:7], v[172:173]
	s_waitcnt lgkmcnt(0)
	v_pk_mul_f32 v[2:3], v[2:3], v[222:223]
	v_pk_mul_f32 v[0:1], v[0:1], v[220:221]
	v_pk_mul_f32 v[60:61], v[60:61], v[162:163]
	v_pk_mul_f32 v[56:57], v[56:57], v[166:167]
	v_pk_mul_f32 v[52:53], v[52:53], v[170:171]
	v_pk_mul_f32 v[62:63], v[62:63], v[164:165]
	v_pk_mul_f32 v[58:59], v[58:59], v[168:169]
	v_pk_mul_f32 v[54:55], v[54:55], v[172:173]
	v_pk_mul_f32 v[50:51], v[50:51], v[222:223]
	v_pk_mul_f32 v[48:49], v[48:49], v[220:221]
	v_pk_mul_f32 v[44:45], v[44:45], v[162:163]
	v_pk_mul_f32 v[40:41], v[40:41], v[166:167]
	v_pk_mul_f32 v[36:37], v[36:37], v[170:171]
	v_pk_mul_f32 v[46:47], v[46:47], v[164:165]
	v_pk_mul_f32 v[42:43], v[42:43], v[168:169]
	v_pk_mul_f32 v[38:39], v[38:39], v[172:173]
	v_pk_mul_f32 v[34:35], v[34:35], v[222:223]
	v_pk_mul_f32 v[32:33], v[32:33], v[220:221]
	v_pk_mul_f32 v[28:29], v[28:29], v[162:163]
	v_pk_mul_f32 v[24:25], v[24:25], v[166:167]
	v_pk_mul_f32 v[20:21], v[20:21], v[170:171]
	v_pk_mul_f32 v[30:31], v[30:31], v[164:165]
	v_pk_mul_f32 v[26:27], v[26:27], v[168:169]
	v_pk_mul_f32 v[22:23], v[22:23], v[172:173]
	v_pk_mul_f32 v[18:19], v[18:19], v[222:223]
	v_pk_mul_f32 v[16:17], v[16:17], v[220:221]

; __device__ __forceinline__ void partialSM(f32x16& p0, f32x16& p1, float& m_reg, float& mn, float& alpha) {
;   constexpr float C = SCALE * 1.4426950408889634f;
;   float pmax = p0[0];
; #pragma unroll
;   for (int r = 1; r < 16; ++r) pmax = fmaxf(pmax, p0[r]);
; #pragma unroll
;   for (int r = 0; r < 16; ++r) pmax = fmaxf(pmax, p1[r]);
;   { auto rr = __builtin_amdgcn_permlane32_swap(__float_as_uint(pmax), __float_as_uint(pmax), false, false);
;     pmax = fmaxf(__uint_as_float(rr[0]), __uint_as_float(rr[1])); }
; template <int DA, int DB> __device__ __forceinline__ void pv_pair(f32x16& oa, f32x16& ob, int vb, bf16x8 pa0, bf16x8 pa1, bf16x8 pa2, bf16x8 pa3) {
;     ...
;   { const s16x4 al0 = tr_read<v_rd_off(DA, 0, 0)>(vb), ah0 = tr_read<v_rd_off(DA, 0, 1)>(vb), al1 = tr_read<v_rd_off(DA, 1, 0)>(vb), ah1 = tr_read<v_rd_off(DA, 1, 1)>(vb);
;     const s16x4 bl0 = tr_read<v_rd_off(DB, 0, 0)>(vb), bh0 = tr_read<v_rd_off(DB, 0, 1)>(vb), bl1 = tr_read<v_rd_off(DB, 1, 0)>(vb), bh1 = tr_read<v_rd_off(DB, 1, 1)>(vb);
;     asm volatile("s_waitcnt lgkmcnt(0)" ::: "memory"); SBAR();
;     oa = __builtin_amdgcn_mfma_f32_32x32x16_bf16(pa0, PK(al0, ah0), oa, 0, 0, 0); ob = __builtin_amdgcn_mfma_f32_32x32x16_bf16(pa0, PK(bl0, bh0), ob, 0, 0, 0);
;     oa = __builtin_amdgcn_mfma_f32_32x32x16_bf16(pa1, PK(al1, ah1), oa, 0, 0, 0); ob = __builtin_amdgcn_mfma_f32_32x32x16_bf16(pa1, PK(bl1, bh1), ob, 0, 0, 0); }
;   { const s16x4 al2 = tr_read<v_rd_off(DA, 2, 0)>(vb), ah2 = tr_read<v_rd_off(DA, 2, 1)>(vb), al3 = tr_read<v_rd_off(DA, 3, 0)>(vb), ah3 = tr_read<v_rd_off(DA, 3, 1)>(vb);
;     const s16x4 bl2 = tr_read<v_rd_off(DB, 2, 0)>(vb), bh2 = tr_read<v_rd_off(DB, 2, 1)>(vb), bl3 = tr_read<v_rd_off(DB, 3, 0)>(vb), bh3 = tr_read<v_rd_off(DB, 3, 1)>(vb);
;     asm volatile("s_waitcnt lgkmcnt(0)" ::: "memory"); SBAR();
;     oa = __builtin_amdgcn_mfma_f32_32x32x16_bf16(pa2, PK(al2, ah2), oa, 0, 0, 0); ob = __builtin_amdgcn_mfma_f32_32x32x16_bf16(pa2, PK(bl2, bh2), ob, 0, 0, 0);
;     oa = __builtin_amdgcn_mfma_f32_32x32x16_bf16(pa3, PK(al3, ah3), oa, 0, 0, 0); ob = __builtin_amdgcn_mfma_f32_32x32x16_bf16(pa3, PK(bl3, bh3), ob, 0, 0, 0); }
;     ...
; }
; __device__ __forceinline__ void pv_d0(f32x16* o, int vb, bf16x8 pa0, bf16x8 pa1, bf16x8 pa2, bf16x8 pa3) {
;   pv_pair<0, 1>(o[0], o[1], vb, pa0, pa1, pa2, pa3); pv_pair<2, 3>(o[2], o[3], vb, pa0, pa1, pa2, pa3);
.LBB0_1530:
	ds_read_b64_tr_b16 v[190:191], v199 offset:0
	ds_read_b64_tr_b16 v[192:193], v199 offset:0x800
	ds_read_b64_tr_b16 v[224:225], v199 offset:0x1000
	ds_read_b64_tr_b16 v[226:227], v199 offset:0x1800
	ds_read_b64_tr_b16 v[228:229], v199 offset:0x200
	ds_read_b64_tr_b16 v[230:231], v199 offset:0xa00
	ds_read_b64_tr_b16 v[232:233], v199 offset:0x1200
	ds_read_b64_tr_b16 v[234:235], v199 offset:0x1a00
	s_nop 0
	s_waitcnt lgkmcnt(6)
	v_mfma_f32_32x32x16_bf16 v[0:15], v[172:175], v[190:193], v[0:15]
	ds_read_b64_tr_b16 v[190:191], v199 offset:0x2000
	ds_read_b64_tr_b16 v[192:193], v199 offset:0x2800
	s_waitcnt lgkmcnt(4)
	v_mfma_f32_32x32x16_bf16 v[48:63], v[172:175], v[228:231], v[48:63]
	v_mfma_f32_32x32x16_bf16 v[0:15], v[168:171], v[224:227], v[0:15]
	ds_read_b64_tr_b16 v[224:225], v199 offset:0x3000
	ds_read_b64_tr_b16 v[226:227], v199 offset:0x3800
	ds_read_b64_tr_b16 v[228:229], v199 offset:0x2200
	ds_read_b64_tr_b16 v[230:231], v199 offset:0x2a00
	ds_read_b64_tr_b16 v[236:237], v199 offset:0x3200
	ds_read_b64_tr_b16 v[238:239], v199 offset:0x3a00
	s_waitcnt lgkmcnt(8)
	v_mfma_f32_32x32x16_bf16 v[48:63], v[168:171], v[232:235], v[48:63]
	s_waitcnt lgkmcnt(6)
	v_mfma_f32_32x32x16_bf16 v[0:15], v[164:167], v[190:193], v[0:15]
	ds_read_b64_tr_b16 v[190:191], v199 offset:0x400
	ds_read_b64_tr_b16 v[192:193], v199 offset:0xc00
	s_waitcnt lgkmcnt(4)
	v_mfma_f32_32x32x16_bf16 v[48:63], v[164:167], v[228:231], v[48:63]
	v_mfma_f32_32x32x16_bf16 v[0:15], v[160:163], v[224:227], v[0:15]
	ds_read_b64_tr_b16 v[224:225], v199 offset:0x1400
	ds_read_b64_tr_b16 v[226:227], v199 offset:0x1c00
	ds_read_b64_tr_b16 v[228:229], v199 offset:0x600
	ds_read_b64_tr_b16 v[230:231], v199 offset:0xe00
	ds_read_b64_tr_b16 v[232:233], v199 offset:0x1600
	ds_read_b64_tr_b16 v[234:235], v199 offset:0x1e00
	s_waitcnt lgkmcnt(8)
	v_mfma_f32_32x32x16_bf16 v[48:63], v[160:163], v[236:239], v[48:63]
	s_waitcnt lgkmcnt(6)
	v_mfma_f32_32x32x16_bf16 v[32:47], v[172:175], v[190:193], v[32:47]
	s_waitcnt lgkmcnt(2)
	v_mfma_f32_32x32x16_bf16 v[16:31], v[172:175], v[228:231], v[16:31]
	ds_read_b64_tr_b16 v[172:173], v199 offset:0x2400
	ds_read_b64_tr_b16 v[174:175], v199 offset:0x2c00
	ds_read_b64_tr_b16 v[190:191], v199 offset:0x3400
	ds_read_b64_tr_b16 v[192:193], v199 offset:0x3c00
	v_mfma_f32_32x32x16_bf16 v[32:47], v[168:171], v[224:227], v[32:47]
	ds_read_b64_tr_b16 v[224:225], v199 offset:0x2600
	ds_read_b64_tr_b16 v[226:227], v199 offset:0x2e00
	ds_read_b64_tr_b16 v[228:229], v199 offset:0x3600
	ds_read_b64_tr_b16 v[230:231], v199 offset:0x3e00
	s_waitcnt lgkmcnt(8)
	v_mfma_f32_32x32x16_bf16 v[16:31], v[168:171], v[232:235], v[16:31]
	v_max_f32_e32 v168, v81, v81
	v_max_f32_e32 v169, v80, v80
	v_max_f32_e32 v168, v169, v168
	v_max3_f32 v168, v168, v82, v83
	v_max3_f32 v168, v168, v84, v85
	v_max3_f32 v168, v168, v86, v87
	v_max3_f32 v168, v168, v88, v89
	v_max3_f32 v168, v168, v90, v91
	v_max3_f32 v168, v168, v92, v93
	v_max3_f32 v168, v168, v94, v95
	v_max3_f32 v168, v168, v64, v65
	v_max3_f32 v168, v168, v66, v67
	s_waitcnt lgkmcnt(6)
	v_mfma_f32_32x32x16_bf16 v[32:47], v[164:167], v[172:175], v[32:47]
	s_waitcnt lgkmcnt(0)
	s_barrier
	s_waitcnt vmcnt(4)
	s_waitcnt vmcnt(3)
	ds_write_b128 v200, v[144:147] offset:16384
	s_waitcnt vmcnt(2)
	ds_write_b128 v201, v[148:151] offset:16384
	s_waitcnt vmcnt(1)
	ds_write_b128 v202, v[152:155] offset:49152
	s_waitcnt vmcnt(0)
	ds_write_b128 v203, v[156:159] offset:49152
	v_mfma_f32_32x32x16_bf16 v[16:31], v[164:167], v[224:227], v[16:31]
	v_max3_f32 v164, v168, v68, v69
	v_max3_f32 v164, v164, v70, v71
	v_max3_f32 v164, v164, v72, v73
	v_max3_f32 v164, v164, v74, v75
	v_max3_f32 v164, v164, v76, v77
	v_max3_f32 v164, v164, v78, v79
	v_mov_b32_e32 v165, v164
	s_nop 1
	v_permlane32_swap_b32_e32 v164, v165
	v_max_f32_e32 v165, v165, v165
	v_max_f32_e32 v164, v164, v164
	v_max_f32_e32 v164, v164, v165
	v_max_f32_e32 v166, v220, v220
	v_sub_f32_e32 v165, v164, v220
	v_max_f32_e32 v164, v166, v164
	v_mfma_f32_32x32x16_bf16 v[32:47], v[160:163], v[190:193], v[32:47]
	v_cmp_ge_f32_e32 vcc, s62, v165
	s_cmp_eq_u64 vcc, exec
	s_cselect_b64 s[6:7], -1, 0
	v_mfma_f32_32x32x16_bf16 v[16:31], v[160:163], v[228:231], v[16:31]
	v_sub_f32_e32 v160, v220, v164
	v_mul_f32_e32 v160, 0x3e0293ee, v160
	v_exp_f32_e32 v160, v160
	s_nop 0
	v_cndmask_b32_e64 v161, v160, 1.0, s[6:7]
	v_cmp_gt_f32_e32 vcc, 1.0, v161
	s_cbranch_vccz .LBB0_1534
	s_and_saveexec_b64 s[22:23], s[4:5]
	ds_write_b32 v198, v161 offset:128
	s_or_b64 exec, exec, s[22:23]
	s_waitcnt lgkmcnt(0)
	v_add_u32_e32 v156, v195, v197
	ds_read_b128 v[144:147], v156 offset:224
	ds_read_b128 v[148:151], v156 offset:192
	ds_read_b128 v[152:155], v156 offset:160
	ds_read_b128 v[156:159], v156 offset:128
	s_waitcnt lgkmcnt(3)
	v_pk_mul_f32 v[12:13], v[12:13], v[144:145]
	s_waitcnt lgkmcnt(2)
	v_pk_mul_f32 v[8:9], v[8:9], v[148:149]
	s_waitcnt lgkmcnt(1)
	v_pk_mul_f32 v[4:5], v[4:5], v[152:153]
	v_pk_mul_f32 v[14:15], v[14:15], v[146:147]
	v_pk_mul_f32 v[10:11], v[10:11], v[150:151]
	v_pk_mul_f32 v[6:7], v[6:7], v[154:155]
	s_waitcnt lgkmcnt(0)
	v_pk_mul_f32 v[2:3], v[2:3], v[158:159]
	v_pk_mul_f32 v[0:1], v[0:1], v[156:157]
	v_pk_mul_f32 v[60:61], v[60:61], v[144:145]
	v_pk_mul_f32 v[56:57], v[56:57], v[148:149]
	v_pk_mul_f32 v[52:53], v[52:53], v[152:153]
	v_pk_mul_f32 v[62:63], v[62:63], v[146:147]
	v_pk_mul_f32 v[58:59], v[58:59], v[150:151]
	v_pk_mul_f32 v[54:55], v[54:55], v[154:155]
	v_pk_mul_f32 v[50:51], v[50:51], v[158:159]
	v_pk_mul_f32 v[48:49], v[48:49], v[156:157]
	v_pk_mul_f32 v[44:45], v[44:45], v[144:145]
	v_pk_mul_f32 v[40:41], v[40:41], v[148:149]
	v_pk_mul_f32 v[36:37], v[36:37], v[152:153]
	v_pk_mul_f32 v[46:47], v[46:47], v[146:147]
	v_pk_mul_f32 v[42:43], v[42:43], v[150:151]
	v_pk_mul_f32 v[38:39], v[38:39], v[154:155]
	v_pk_mul_f32 v[34:35], v[34:35], v[158:159]
	v_pk_mul_f32 v[32:33], v[32:33], v[156:157]
	v_pk_mul_f32 v[28:29], v[28:29], v[144:145]
	v_pk_mul_f32 v[24:25], v[24:25], v[148:149]
	v_pk_mul_f32 v[20:21], v[20:21], v[152:153]
	v_pk_mul_f32 v[30:31], v[30:31], v[146:147]
	v_pk_mul_f32 v[26:27], v[26:27], v[150:151]
	v_pk_mul_f32 v[22:23], v[22:23], v[154:155]
	v_pk_mul_f32 v[18:19], v[18:19], v[158:159]
	v_pk_mul_f32 v[16:17], v[16:17], v[156:157]
